# DA fast loops replaced by one hand-scheduled cross-tile software-pipelined loop (Q one block ahead, P one behind, inline row sums, 2 barriers per tile); same bf16 MFMA + f32 softmax numerics
# speedup vs baseline: 1.0200x; 1.0200x over previous
; __device__ __forceinline__ float fast_exp2(float x) { return __builtin_amdgcn_exp2f(x); }
; __device__ void da_unit(char* lds, const Params& p, int layer, int unit) {
;     ...
;             float ps = 0.f;
; #pragma unroll
;             for (int e = 0; e < 16; ++e) { s[e] = fast_exp2(s[e] - mm); ps += s[e]; }
;             lrow += ps;
;             bf16x8 pb[2];
; #pragma unroll
;             for (int sp = 0; sp < 2; ++sp) {
;                 u32x4 w;
;                 w.x = cvt_pk_bf16(s[8 * sp + 0], s[8 * sp + 1]); w.y = cvt_pk_bf16(s[8 * sp + 2], s[8 * sp + 3]);
;                 w.z = cvt_pk_bf16(s[8 * sp + 4], s[8 * sp + 5]); w.w = cvt_pk_bf16(s[8 * sp + 6], s[8 * sp + 7]);
;                 pb[sp] = __builtin_bit_cast(bf16x8, w);
;             }
; #pragma unroll
;             for (int sp = 0; sp < 2; ++sp)
; #pragma unroll
;                 for (int k = 0; k < 4; ++k) {
;                     const bf16x8 vf = *(const bf16x8*)(cV + (kb >> 1) * DA_VSUB + (32 * k + r) * DA_VP + (32 * (kb & 1) + 16 * sp + 8 * h2) * 2);
;                     O[k] = __builtin_amdgcn_mfma_f32_32x32x16_bf16(vf, pb[sp], O[k], 0, 0, 0);
;                 }
;         }
;         if (it + 1 < NT) {
; #pragma unroll
;             for (int j = 0; j < 4; ++j) {
;                 *(u32x4*)(nK + (kr_ + 32 * j) * DA_KP + kc_ * 16) = rk[j];
;                 *(u32x4*)(nK + DA_KBYTES + (j >> 1) * DA_VSUB + (vr_ + 64 * (j & 1)) * DA_VP + vc_ * 16) = rv[j];
;             }
;         }
;         __syncthreads();
;     }
.LBB0_486:
	v_sub_f32_e32 v72, v110, v169
	v_exp_f32_e32 v99, v72
	v_sub_f32_e32 v72, v108, v169
	v_exp_f32_e32 v156, v72
	v_sub_f32_e32 v72, v111, v169
	v_exp_f32_e32 v157, v72
	v_sub_f32_e32 v72, v109, v169
	ds_read_b128 v[110:113], v100 offset:57920
	ds_read_b128 v[174:177], v100 offset:62528
	v_exp_f32_e32 v158, v72
	v_sub_f32_e32 v72, v107, v169
	v_exp_f32_e32 v159, v72
	v_sub_f32_e32 v72, v106, v169
	v_exp_f32_e32 v160, v72
	v_sub_f32_e32 v71, v71, v169
	ds_read_b128 v[72:75], v100 offset:53312
	v_sub_f32_e32 v70, v70, v169
	v_exp_f32_e32 v161, v71
	v_exp_f32_e32 v162, v70
	v_sub_f32_e32 v81, v105, v169
	v_exp_f32_e32 v163, v81
	v_sub_f32_e32 v81, v102, v169
	v_exp_f32_e32 v178, v81
	v_sub_f32_e32 v81, v103, v169
	v_exp_f32_e32 v179, v81
	v_sub_f32_e32 v81, v104, v169
	ds_read_b128 v[102:105], v101 offset:53312
	s_mov_b32 s2, -2.0
	v_cvt_pk_bf16_f32 v106, v99, v156
	v_cvt_pk_bf16_f32 v107, v157, v158
	v_cvt_pk_bf16_f32 v108, v159, v160
	v_cvt_pk_bf16_f32 v109, v161, v162
	v_sub_f32_e32 v78, v78, v169
	v_mov_b32_e32 v64, v65
	s_mov_b32 s3, 0xc0400000
	s_waitcnt lgkmcnt(2)
	v_mfma_f32_32x32x16_bf16 v[16:31], v[174:177], v[106:109], v[16:31]
	v_exp_f32_e32 v174, v78
	v_sub_f32_e32 v78, v79, v169
	v_pk_mul_f32 v[68:69], v[64:65], s[2:3] op_sel_hi:[0,1]
	s_mov_b32 s2, -4.0
	v_exp_f32_e32 v175, v78
	v_sub_f32_e32 v78, v80, v169
	s_mov_b32 s3, 0xc0a00000
	v_exp_f32_e32 v191, v81
	v_exp_f32_e32 v176, v78
	ds_read_b128 v[78:81], v100 offset:53344
	s_waitcnt lgkmcnt(2)
	v_mfma_f32_32x32x16_bf16 v[48:63], v[72:75], v[106:109], v[48:63]
	v_mul_f32_e64 v70, v64, s2
	v_mul_f32_e64 v71, v64, s3
	s_mov_b32 s2, 0xc0c00000
	s_mov_b32 s3, 0xc0e00000
	v_mul_f32_e64 v72, v64, s2
	v_mul_f32_e64 v73, v64, s3
	s_mov_b32 s2, 0xc1800000
	v_sub_f32_e32 v67, v67, v169
	s_mov_b32 s3, 0xc1880000
	v_exp_f32_e32 v67, v67
	v_pk_mul_f32 v[74:75], v[64:65], s[2:3] op_sel_hi:[0,1]
	s_mov_b32 s2, 0xc1900000
	v_mfma_f32_32x32x16_bf16 v[32:47], v[110:113], v[106:109], v[32:47]
	s_mov_b32 s3, 0xc1980000
	v_mul_f32_e64 v76, v64, s2
	v_mul_f32_e64 v77, v64, s3
	s_mov_b32 s2, 0xc1a00000
	s_mov_b32 s3, 0xc1a80000
	ds_read_b128 v[110:113], v100 offset:62560
	v_readlane_b32 s1, v254, 50
	v_mul_f32_e32 v66, 0x80000000, v65
	s_waitcnt lgkmcnt(2)
	v_mfma_f32_32x32x16_bf16 v[0:15], v[102:105], v[106:109], v[0:15]
	ds_read_b128 v[106:109], v100 offset:57952
	v_cvt_pk_bf16_f32 v102, v163, v178
	v_cvt_pk_bf16_f32 v103, v179, v191
	v_cvt_pk_bf16_f32 v104, v174, v175
	v_cvt_pk_bf16_f32 v105, v176, v67
	s_sub_i32 s9, 16, s14
	s_andn2_b64 vcc, exec, s[4:5]
	s_waitcnt lgkmcnt(2)
	v_mfma_f32_32x32x16_bf16 v[48:63], v[78:81], v[102:105], v[48:63]
	v_mul_f32_e64 v78, v64, s2
	v_mul_f32_e64 v79, v64, s3
	s_mov_b32 s2, 0xc1b00000
	s_mov_b32 s3, 0xc1b80000
	v_mul_f32_e64 v80, v64, s2
	v_mul_f32_e64 v81, v64, s3
	v_add_f32_e32 v64, 0, v99
	v_add_f32_e32 v64, v156, v64
	v_add_f32_e32 v64, v157, v64
	s_waitcnt lgkmcnt(0)
	v_mfma_f32_32x32x16_bf16 v[32:47], v[106:109], v[102:105], v[32:47]
	v_add_f32_e32 v64, v158, v64
	ds_read_b128 v[106:109], v101 offset:53344
	v_add_f32_e32 v64, v159, v64
	v_add_f32_e32 v64, v160, v64
	v_add_f32_e32 v64, v161, v64
	v_add_f32_e32 v64, v162, v64
	v_add_f32_e32 v64, v163, v64
	v_add_f32_e32 v64, v178, v64
	v_add_f32_e32 v64, v179, v64
	v_add_f32_e32 v64, v191, v64
	v_mfma_f32_32x32x16_bf16 v[16:31], v[110:113], v[102:105], v[16:31]
	v_add_f32_e32 v64, v174, v64
	v_add_f32_e32 v64, v175, v64
	v_add_f32_e32 v64, v176, v64
	v_add_f32_e32 v64, v67, v64
	v_add3_u32 v67, s1, v180, v182
	s_add_i32 s1, 0, 0x1a000
	v_add3_u32 v99, s1, v183, v181
	s_waitcnt lgkmcnt(0)
	v_mfma_f32_32x32x16_bf16 v[0:15], v[106:109], v[102:105], v[0:15]
	s_waitcnt vmcnt(7)
	ds_write_b128 v67, v[130:133]
	s_waitcnt vmcnt(6)
	ds_write_b128 v99, v[82:85]
	s_waitcnt vmcnt(5)
	ds_write_b128 v67, v[134:137] offset:8704
	v_add3_u32 v82, s1, v181, v183
	v_readlane_b32 s1, v254, 51
	s_waitcnt vmcnt(4)
	ds_write_b128 v82, v[86:89] offset:9216
	s_waitcnt vmcnt(3)
	ds_write_b128 v67, v[138:141] offset:17408
	v_add3_u32 v82, s1, v183, v181
	s_waitcnt vmcnt(2)
	ds_write_b128 v82, v[90:93]
	s_waitcnt vmcnt(1)
	ds_write_b128 v67, v[142:145] offset:26112
	v_add3_u32 v67, s1, v181, v183
	v_add_f32_e32 v193, v98, v64
	s_waitcnt vmcnt(0)
	ds_write_b128 v67, v[94:97] offset:9216
	s_waitcnt lgkmcnt(0)
	s_barrier
	v_xor_b32_e32 v67, 0x80000000, v65
	v_mul_f32_e32 v64, 0xc2000000, v65
	v_mov_b32_e32 v250, v65
	v_mov_b32_e32 v191, 0
	v_mov_b32_e32 v192, 0
	v_mov_b32_e32 v202, 0
	v_mov_b32_e32 v203, 0
	v_mov_b32_e32 v204, 0
	v_mov_b32_e32 v205, 0
	v_mov_b32_e32 v206, 0
	v_mov_b32_e32 v207, 0
	v_mov_b32_e32 v208, 0
	v_mov_b32_e32 v209, 0
	s_cmp_lg_u32 s9, 1
	s_cbranch_scc1 .Lda_p_noflip
	v_xor_b32_e32 v66, 0x80000000, v66
	v_xor_b32_e32 v67, 0x80000000, v67
	v_xor_b32_e32 v68, 0x80000000, v68
	v_xor_b32_e32 v69, 0x80000000, v69
	v_xor_b32_e32 v70, 0x80000000, v70
	v_xor_b32_e32 v71, 0x80000000, v71
	v_xor_b32_e32 v72, 0x80000000, v72
	v_xor_b32_e32 v73, 0x80000000, v73
	v_xor_b32_e32 v74, 0x80000000, v74
	v_xor_b32_e32 v75, 0x80000000, v75
	v_xor_b32_e32 v76, 0x80000000, v76
	v_xor_b32_e32 v77, 0x80000000, v77
	v_xor_b32_e32 v78, 0x80000000, v78
	v_xor_b32_e32 v79, 0x80000000, v79
	v_xor_b32_e32 v80, 0x80000000, v80
	v_xor_b32_e32 v81, 0x80000000, v81
; __device__ void da_unit(char* lds, const Params& p, int layer, int unit) {
;     ...
;     for (int it = 1; it < NT - qb; ++it) {
;         const int kt = tile_of(it);
;         const char* cK = lds + (it & 1) * DA_STAGE;
;         const char* cV = cK + DA_KBYTES;
;         char* nK = lds + ((it + 1) & 1) * DA_STAGE;
;         const int tn = tile_of(it + 1 < NT ? it + 1 : it);
;         if (it + 1 < NT) {
; #pragma unroll
;             for (int j = 0; j < 4; ++j) rk[j] = *(const u32x4*)(Kg + (size_t)tn * 16384 + j * 4096);
;         }
;     ...
;         DA_FAST_HALF(Bs, -slope2, 0)
;         if (it + 1 < NT) {
; #pragma unroll
;             for (int j = 0; j < 4; ++j) *(u32x4*)(nK + (kr_ + 32 * j) * DA_KP + kc_ * 16) = rk[j];
; #pragma unroll
;             for (int j = 0; j < 4; ++j) rk[j] = *(const u32x4*)(Vg + (size_t)tn * 16384 + j * 4096);
;         }
;         DA_FAST_HALF(Bs, -slope2, 1)
.Lda_p_noflip:
	s_add_i32 s1, s8, 0x11800
	v_add3_u32 v234, s1, v186, v152
	s_mov_b32 s2, 0x8800
	v_add3_u32 v178, s2, v152, v154
	ds_read_b128 v[210:213], v234 offset:0
	ds_read_b128 v[214:217], v234 offset:32
	ds_read_b128 v[218:221], v234 offset:64
	ds_read_b128 v[222:225], v234 offset:96
	ds_read_b128 v[226:229], v178 offset:18496
	ds_read_b128 v[230:233], v178 offset:23104
	ds_read_b128 v[174:177], v178 offset:27712
	ds_read_b128 v[246:249], v178 offset:32320
	s_add_i32 s0, s14, 2
	s_cmp_lt_u32 2, s9
	s_cselect_b32 s0, s0, 13
	s_lshl_b32 s18, s0, 15
	s_mov_b32 s19, 0
	v_lshl_add_u64 v[156:157], v[148:149], 0, s[18:19]
	global_load_dwordx4 v[130:133], v[156:157], off
	s_add_u32 s18, s18, 0x2000
	v_lshl_add_u64 v[156:157], v[148:149], 0, s[18:19]
	global_load_dwordx4 v[134:137], v[156:157], off
	s_add_u32 s18, s18, 0x2000
	v_lshl_add_u64 v[156:157], v[148:149], 0, s[18:19]
	global_load_dwordx4 v[138:141], v[156:157], off
	s_add_u32 s18, s18, 0x2000
	v_lshl_add_u64 v[156:157], v[148:149], 0, s[18:19]
	global_load_dwordx4 v[142:145], v[156:157], off
	s_waitcnt lgkmcnt(7)
	v_mfma_f32_32x32x16_bf16 v[82:97], v[210:213], v[114:117], v[66:81]
	ds_read_b128 v[210:213], v234 offset:8704
	s_waitcnt lgkmcnt(7)
	v_mfma_f32_32x32x16_bf16 v[82:97], v[214:217], v[118:121], v[82:97]
	ds_read_b128 v[214:217], v234 offset:8736
	s_waitcnt lgkmcnt(7)
	v_mfma_f32_32x32x16_bf16 v[82:97], v[218:221], v[122:125], v[82:97]
	ds_read_b128 v[218:221], v234 offset:8768
	s_waitcnt lgkmcnt(7)
	v_mfma_f32_32x32x16_bf16 v[82:97], v[222:225], v[126:129], v[82:97]
	ds_read_b128 v[222:225], v234 offset:8800
	s_mov_b32 s4, 1
	s_waitcnt lgkmcnt(0)
.Lda_top:
	s_cmp_lg_u32 s4, s9
	s_cbranch_scc1 .Lda_noflip
	v_xor_b32_e32 v64, 0x80000000, v64
	v_xor_b32_e32 v250, 0x80000000, v250
.Lda_noflip:
	s_add_i32 s0, s14, s4
	s_sub_i32 s1, 15, s4
	s_cmp_lt_u32 s4, s9
	s_cselect_b32 s10, s0, s1
	s_lshl_b32 s11, s10, 7
	s_add_i32 s16, s4, 1
	s_add_i32 s0, s14, s16
	s_sub_i32 s1, 15, s16
	s_cmp_lt_u32 s16, s9
	s_cselect_b32 s0, s0, s1
	s_add_i32 s16, s4, 2
	s_add_i32 s3, s14, s16
	s_sub_i32 s1, 15, s16
	s_cmp_lt_u32 s16, s9
	s_cselect_b32 s3, s3, s1
	s_bitcmp1_b32 s4, 0
	s_cselect_b32 s17, 0x11800, 0
	s_sub_i32 s5, 0x11800, s17
	s_add_i32 s1, s17, s8
	s_add_i32 s2, s17, 0x8800
	v_add3_u32 v234, s1, v186, v152
	v_add3_u32 v235, s2, v152, v154
	s_add_i32 s1, s5, s8
	s_add_i32 s2, s5, 0x8800
	v_add3_u32 v236, s1, v186, v152
	v_add3_u32 v178, s2, v152, v154
	v_cvt_f32_u32_e32 v242, s11
	v_add_f32_e32 v242, v185, v242
	v_fma_f32 v239, v242, v250, v169
	v_fma_f32 v253, v242, -v250, v64
	v_sub_f32_e32 v241, v169, v253
	v_mfma_f32_32x32x16_bf16 v[98:113], v[210:213], v[114:117], v[66:81]
	ds_read_b128 v[210:213], v234 offset:17408
	v_sub_f32_e32 v82, v82, v239
	v_sub_f32_e32 v83, v83, v239
	v_sub_f32_e32 v84, v84, v239
	v_sub_f32_e32 v85, v85, v239
	v_exp_f32_e32 v82, v82
	v_mfma_f32_32x32x16_bf16 v[48:63], v[226:229], v[202:205], v[48:63]
	ds_read_b128 v[226:229], v178 offset:18528
	v_exp_f32_e32 v83, v83
	v_exp_f32_e32 v84, v84
	v_exp_f32_e32 v85, v85
	v_mfma_f32_32x32x16_bf16 v[32:47], v[230:233], v[202:205], v[32:47]
	ds_read_b128 v[230:233], v178 offset:23136
	v_add_f32_e32 v191, v191, v82
	v_add_f32_e32 v192, v192, v83
	v_cvt_pk_bf16_f32 v194, v82, v83
	v_add_f32_e32 v191, v191, v84
	v_add_f32_e32 v192, v192, v85
	v_cvt_pk_bf16_f32 v195, v84, v85
	v_mfma_f32_32x32x16_bf16 v[98:113], v[214:217], v[118:121], v[98:113]
	ds_read_b128 v[214:217], v234 offset:17440
	v_sub_f32_e32 v86, v86, v239
	v_sub_f32_e32 v87, v87, v239
	v_sub_f32_e32 v88, v88, v239
	v_sub_f32_e32 v89, v89, v239
	v_exp_f32_e32 v86, v86
	v_mfma_f32_32x32x16_bf16 v[16:31], v[174:177], v[202:205], v[16:31]
	ds_read_b128 v[174:177], v178 offset:27744
	v_exp_f32_e32 v87, v87
	v_exp_f32_e32 v88, v88
	v_exp_f32_e32 v89, v89
	v_mfma_f32_32x32x16_bf16 v[0:15], v[246:249], v[202:205], v[0:15]
	ds_read_b128 v[246:249], v178 offset:32352
	v_add_f32_e32 v191, v191, v86
	v_add_f32_e32 v192, v192, v87
	v_cvt_pk_bf16_f32 v196, v86, v87
	v_add_f32_e32 v191, v191, v88
	v_add_f32_e32 v192, v192, v89
	v_cvt_pk_bf16_f32 v197, v88, v89
	v_mfma_f32_32x32x16_bf16 v[98:113], v[218:221], v[122:125], v[98:113]
	ds_read_b128 v[218:221], v234 offset:17472
	v_sub_f32_e32 v90, v90, v239
	v_sub_f32_e32 v91, v91, v239
	v_sub_f32_e32 v92, v92, v239
	v_sub_f32_e32 v93, v93, v239
	v_exp_f32_e32 v90, v90
	s_waitcnt lgkmcnt(5)
	v_mfma_f32_32x32x16_bf16 v[48:63], v[226:229], v[206:209], v[48:63]
	ds_read_b128 v[226:229], v235 offset:0
	v_exp_f32_e32 v91, v91
	v_exp_f32_e32 v92, v92
	v_exp_f32_e32 v93, v93
	s_waitcnt lgkmcnt(5)
	v_mfma_f32_32x32x16_bf16 v[32:47], v[230:233], v[206:209], v[32:47]
	ds_read_b128 v[230:233], v235 offset:4608
	v_add_f32_e32 v191, v191, v90
	v_add_f32_e32 v192, v192, v91
	v_cvt_pk_bf16_f32 v198, v90, v91
	v_add_f32_e32 v191, v191, v92
	v_add_f32_e32 v192, v192, v93
	v_cvt_pk_bf16_f32 v199, v92, v93
	v_mfma_f32_32x32x16_bf16 v[98:113], v[222:225], v[126:129], v[98:113]
	ds_read_b128 v[222:225], v234 offset:17504
	v_sub_f32_e32 v94, v94, v239
	v_sub_f32_e32 v95, v95, v239
	v_sub_f32_e32 v96, v96, v239
	v_sub_f32_e32 v97, v97, v239
	v_exp_f32_e32 v94, v94
	s_waitcnt lgkmcnt(5)
	v_mfma_f32_32x32x16_bf16 v[16:31], v[174:177], v[206:209], v[16:31]
	ds_read_b128 v[174:177], v235 offset:9216
	v_exp_f32_e32 v95, v95
	v_exp_f32_e32 v96, v96
	v_exp_f32_e32 v97, v97
	s_waitcnt lgkmcnt(5)
	v_mfma_f32_32x32x16_bf16 v[0:15], v[246:249], v[206:209], v[0:15]
	ds_read_b128 v[246:249], v235 offset:13824
	v_add_f32_e32 v191, v191, v94
	v_add_f32_e32 v192, v192, v95
	v_cvt_pk_bf16_f32 v200, v94, v95
	v_add_f32_e32 v191, v191, v96
	v_add_f32_e32 v192, v192, v97
	v_cvt_pk_bf16_f32 v201, v96, v97
	s_waitcnt lgkmcnt(0)
	s_barrier
	s_cmp_lt_u32 s4, 15
	s_cbranch_scc0 .Lda_nokw
	v_add3_u32 v158, s5, v180, v182
	s_waitcnt vmcnt(3)
	ds_write_b128 v158, v[130:133] offset:0
	s_waitcnt vmcnt(2)
	ds_write_b128 v158, v[134:137] offset:8704
	s_waitcnt vmcnt(1)
	ds_write_b128 v158, v[138:141] offset:17408
	s_waitcnt vmcnt(0)
	ds_write_b128 v158, v[142:145] offset:26112
	s_lshl_b32 s18, s0, 15
	s_mov_b32 s19, 0
	v_lshl_add_u64 v[156:157], v[150:151], 0, s[18:19]
	global_load_dwordx4 v[130:133], v[156:157], off
	s_add_u32 s18, s18, 0x2000
	v_lshl_add_u64 v[156:157], v[150:151], 0, s[18:19]
	global_load_dwordx4 v[134:137], v[156:157], off
	s_add_u32 s18, s18, 0x2000
	v_lshl_add_u64 v[156:157], v[150:151], 0, s[18:19]
	global_load_dwordx4 v[138:141], v[156:157], off
	s_add_u32 s18, s18, 0x2000
	v_lshl_add_u64 v[156:157], v[150:151], 0, s[18:19]
	global_load_dwordx4 v[142:145], v[156:157], off
; __device__ void da_unit(char* lds, const Params& p, int layer, int unit) {
;     ...
;         DA_FAST_HALF(Bs, -slope2, 0)
;         if (it + 1 < NT) {
; #pragma unroll
;             for (int j = 0; j < 4; ++j) *(u32x4*)(nK + (kr_ + 32 * j) * DA_KP + kc_ * 16) = rk[j];
; #pragma unroll
;             for (int j = 0; j < 4; ++j) rk[j] = *(const u32x4*)(Vg + (size_t)tn * 16384 + j * 4096);
;         }
;         DA_FAST_HALF(Bs, -slope2, 1)
;     ...
;         if (it + 1 < NT) {
; #pragma unroll
;             for (int j = 0; j < 4; ++j) *(u32x4*)(nK + DA_KBYTES + (j >> 1) * DA_VSUB + (vr_ + 64 * (j & 1)) * DA_VP + vc_ * 16) = rk[j];
.Lda_nokw:
	v_mfma_f32_32x32x16_bf16 v[82:97], v[210:213], v[114:117], v[66:81]
	ds_read_b128 v[210:213], v234 offset:26112
	v_sub_f32_e32 v98, v98, v241
	v_sub_f32_e32 v99, v99, v241
	v_sub_f32_e32 v100, v100, v241
	v_sub_f32_e32 v101, v101, v241
	v_exp_f32_e32 v98, v98
	v_mfma_f32_32x32x16_bf16 v[48:63], v[226:229], v[194:197], v[48:63]
	ds_read_b128 v[226:229], v235 offset:32
	v_exp_f32_e32 v99, v99
	v_exp_f32_e32 v100, v100
	v_exp_f32_e32 v101, v101
	v_mfma_f32_32x32x16_bf16 v[32:47], v[230:233], v[194:197], v[32:47]
	ds_read_b128 v[230:233], v235 offset:4640
	v_add_f32_e32 v191, v191, v98
	v_add_f32_e32 v192, v192, v99
	v_cvt_pk_bf16_f32 v202, v98, v99
	v_add_f32_e32 v191, v191, v100
	v_add_f32_e32 v192, v192, v101
	v_cvt_pk_bf16_f32 v203, v100, v101
	v_mfma_f32_32x32x16_bf16 v[82:97], v[214:217], v[118:121], v[82:97]
	ds_read_b128 v[214:217], v234 offset:26144
	v_sub_f32_e32 v102, v102, v241
	v_sub_f32_e32 v103, v103, v241
	v_sub_f32_e32 v104, v104, v241
	v_sub_f32_e32 v105, v105, v241
	v_exp_f32_e32 v102, v102
	v_mfma_f32_32x32x16_bf16 v[16:31], v[174:177], v[194:197], v[16:31]
	ds_read_b128 v[174:177], v235 offset:9248
	v_exp_f32_e32 v103, v103
	v_exp_f32_e32 v104, v104
	v_exp_f32_e32 v105, v105
	v_mfma_f32_32x32x16_bf16 v[0:15], v[246:249], v[194:197], v[0:15]
	ds_read_b128 v[246:249], v235 offset:13856
	v_add_f32_e32 v191, v191, v102
	v_add_f32_e32 v192, v192, v103
	v_cvt_pk_bf16_f32 v204, v102, v103
	v_add_f32_e32 v191, v191, v104
	v_add_f32_e32 v192, v192, v105
	v_cvt_pk_bf16_f32 v205, v104, v105
	v_mfma_f32_32x32x16_bf16 v[82:97], v[218:221], v[122:125], v[82:97]
	ds_read_b128 v[218:221], v234 offset:26176
	v_sub_f32_e32 v106, v106, v241
	v_sub_f32_e32 v107, v107, v241
	v_sub_f32_e32 v108, v108, v241
	v_sub_f32_e32 v109, v109, v241
	v_exp_f32_e32 v106, v106
	s_waitcnt lgkmcnt(5)
	v_mfma_f32_32x32x16_bf16 v[48:63], v[226:229], v[198:201], v[48:63]
	ds_read_b128 v[226:229], v235 offset:64
	v_exp_f32_e32 v107, v107
	v_exp_f32_e32 v108, v108
	v_exp_f32_e32 v109, v109
	s_waitcnt lgkmcnt(5)
	v_mfma_f32_32x32x16_bf16 v[32:47], v[230:233], v[198:201], v[32:47]
	ds_read_b128 v[230:233], v235 offset:4672
	v_add_f32_e32 v191, v191, v106
	v_add_f32_e32 v192, v192, v107
	v_cvt_pk_bf16_f32 v206, v106, v107
	v_add_f32_e32 v191, v191, v108
	v_add_f32_e32 v192, v192, v109
	v_cvt_pk_bf16_f32 v207, v108, v109
	v_mfma_f32_32x32x16_bf16 v[82:97], v[222:225], v[126:129], v[82:97]
	ds_read_b128 v[222:225], v234 offset:26208
	v_sub_f32_e32 v110, v110, v241
	v_sub_f32_e32 v111, v111, v241
	v_sub_f32_e32 v112, v112, v241
	v_sub_f32_e32 v113, v113, v241
	v_exp_f32_e32 v110, v110
	s_waitcnt lgkmcnt(5)
	v_mfma_f32_32x32x16_bf16 v[16:31], v[174:177], v[198:201], v[16:31]
	ds_read_b128 v[174:177], v235 offset:9280
	v_exp_f32_e32 v111, v111
	v_exp_f32_e32 v112, v112
	v_exp_f32_e32 v113, v113
	s_waitcnt lgkmcnt(5)
	v_mfma_f32_32x32x16_bf16 v[0:15], v[246:249], v[198:201], v[0:15]
	ds_read_b128 v[246:249], v235 offset:13888
	v_add_f32_e32 v191, v191, v110
	v_add_f32_e32 v192, v192, v111
	v_cvt_pk_bf16_f32 v208, v110, v111
	v_add_f32_e32 v191, v191, v112
	v_add_f32_e32 v192, v192, v113
	v_cvt_pk_bf16_f32 v209, v112, v113
	s_or_b32 s2, s11, 64
	v_cvt_f32_u32_e32 v242, s2
	v_add_f32_e32 v242, v185, v242
	v_fma_f32 v239, v242, v250, v169
	v_fma_f32 v253, v242, -v250, v64
	v_sub_f32_e32 v241, v169, v253
	v_mfma_f32_32x32x16_bf16 v[98:113], v[210:213], v[114:117], v[66:81]
	v_sub_f32_e32 v82, v82, v239
	v_sub_f32_e32 v83, v83, v239
	v_sub_f32_e32 v84, v84, v239
	v_sub_f32_e32 v85, v85, v239
	v_exp_f32_e32 v82, v82
	s_waitcnt lgkmcnt(4)
	v_mfma_f32_32x32x16_bf16 v[48:63], v[226:229], v[202:205], v[48:63]
	ds_read_b128 v[226:229], v235 offset:96
	v_exp_f32_e32 v83, v83
	v_exp_f32_e32 v84, v84
	v_exp_f32_e32 v85, v85
	s_waitcnt lgkmcnt(4)
	v_mfma_f32_32x32x16_bf16 v[32:47], v[230:233], v[202:205], v[32:47]
	ds_read_b128 v[230:233], v235 offset:4704
	v_add_f32_e32 v191, v191, v82
	v_add_f32_e32 v192, v192, v83
	v_cvt_pk_bf16_f32 v194, v82, v83
	v_add_f32_e32 v191, v191, v84
	v_add_f32_e32 v192, v192, v85
	v_cvt_pk_bf16_f32 v195, v84, v85
	v_mfma_f32_32x32x16_bf16 v[98:113], v[214:217], v[118:121], v[98:113]
	v_sub_f32_e32 v86, v86, v239
	v_sub_f32_e32 v87, v87, v239
	v_sub_f32_e32 v88, v88, v239
	v_sub_f32_e32 v89, v89, v239
	v_exp_f32_e32 v86, v86
	s_waitcnt lgkmcnt(3)
	v_mfma_f32_32x32x16_bf16 v[16:31], v[174:177], v[202:205], v[16:31]
	ds_read_b128 v[174:177], v235 offset:9312
	v_exp_f32_e32 v87, v87
	v_exp_f32_e32 v88, v88
	v_exp_f32_e32 v89, v89
	s_waitcnt lgkmcnt(3)
	v_mfma_f32_32x32x16_bf16 v[0:15], v[246:249], v[202:205], v[0:15]
	ds_read_b128 v[246:249], v235 offset:13920
	v_add_f32_e32 v191, v191, v86
	v_add_f32_e32 v192, v192, v87
	v_cvt_pk_bf16_f32 v196, v86, v87
	v_add_f32_e32 v191, v191, v88
	v_add_f32_e32 v192, v192, v89
	v_cvt_pk_bf16_f32 v197, v88, v89
	v_mfma_f32_32x32x16_bf16 v[98:113], v[218:221], v[122:125], v[98:113]
	v_sub_f32_e32 v90, v90, v239
	v_sub_f32_e32 v91, v91, v239
	v_sub_f32_e32 v92, v92, v239
	v_sub_f32_e32 v93, v93, v239
	v_exp_f32_e32 v90, v90
	s_waitcnt lgkmcnt(3)
	v_mfma_f32_32x32x16_bf16 v[48:63], v[226:229], v[206:209], v[48:63]
	ds_read_b128 v[226:229], v235 offset:18432
	v_exp_f32_e32 v91, v91
	v_exp_f32_e32 v92, v92
	v_exp_f32_e32 v93, v93
	s_waitcnt lgkmcnt(3)
	v_mfma_f32_32x32x16_bf16 v[32:47], v[230:233], v[206:209], v[32:47]
	ds_read_b128 v[230:233], v235 offset:23040
	v_add_f32_e32 v191, v191, v90
	v_add_f32_e32 v192, v192, v91
	v_cvt_pk_bf16_f32 v198, v90, v91
	v_add_f32_e32 v191, v191, v92
	v_add_f32_e32 v192, v192, v93
	v_cvt_pk_bf16_f32 v199, v92, v93
	v_mfma_f32_32x32x16_bf16 v[98:113], v[222:225], v[126:129], v[98:113]
	v_sub_f32_e32 v94, v94, v239
	v_sub_f32_e32 v95, v95, v239
	v_sub_f32_e32 v96, v96, v239
	v_sub_f32_e32 v97, v97, v239
	v_exp_f32_e32 v94, v94
	s_waitcnt lgkmcnt(3)
	v_mfma_f32_32x32x16_bf16 v[16:31], v[174:177], v[206:209], v[16:31]
	ds_read_b128 v[174:177], v235 offset:27648
	v_exp_f32_e32 v95, v95
	v_exp_f32_e32 v96, v96
	v_exp_f32_e32 v97, v97
	s_waitcnt lgkmcnt(3)
	v_mfma_f32_32x32x16_bf16 v[0:15], v[246:249], v[206:209], v[0:15]
	ds_read_b128 v[246:249], v235 offset:32256
	v_add_f32_e32 v191, v191, v94
	v_add_f32_e32 v192, v192, v95
	v_cvt_pk_bf16_f32 v200, v94, v95
	v_add_f32_e32 v191, v191, v96
	v_add_f32_e32 v192, v192, v97
	v_cvt_pk_bf16_f32 v201, v96, v97
	s_cmp_lt_u32 s4, 15
	s_cbranch_scc0 .Lda_novw
	v_add3_u32 v158, s5, v183, v181
	s_waitcnt vmcnt(3)
	ds_write_b128 v158, v[130:133] offset:34816
	s_waitcnt vmcnt(2)
	ds_write_b128 v158, v[134:137] offset:44032
	s_waitcnt vmcnt(1)
	ds_write_b128 v158, v[138:141] offset:53248
	s_waitcnt vmcnt(0)
	ds_write_b128 v158, v[142:145] offset:62464
; __device__ void da_unit(char* lds, const Params& p, int layer, int unit) {
;     ...
;         lam = __expf(s1) - __expf(s2) + p.lam_init[layer];
.Lda_novw:
	s_waitcnt lgkmcnt(0)
	s_barrier
	s_cmp_lt_u32 s4, 14
	s_cbranch_scc0 .Lda_nok
	s_lshl_b32 s18, s3, 15
	s_mov_b32 s19, 0
	v_lshl_add_u64 v[156:157], v[148:149], 0, s[18:19]
	global_load_dwordx4 v[130:133], v[156:157], off
	s_add_u32 s18, s18, 0x2000
	v_lshl_add_u64 v[156:157], v[148:149], 0, s[18:19]
	global_load_dwordx4 v[134:137], v[156:157], off
	s_add_u32 s18, s18, 0x2000
	v_lshl_add_u64 v[156:157], v[148:149], 0, s[18:19]
	global_load_dwordx4 v[138:141], v[156:157], off
	s_add_u32 s18, s18, 0x2000
	v_lshl_add_u64 v[156:157], v[148:149], 0, s[18:19]
	global_load_dwordx4 v[142:145], v[156:157], off
.Lda_nok:
	s_add_i32 s16, s4, 1
	s_cmp_lg_u32 s16, s9
	s_cbranch_scc1 .Lda_nocflip
	v_xor_b32_e32 v66, 0x80000000, v66
	v_xor_b32_e32 v67, 0x80000000, v67
	v_xor_b32_e32 v68, 0x80000000, v68
	v_xor_b32_e32 v69, 0x80000000, v69
	v_xor_b32_e32 v70, 0x80000000, v70
	v_xor_b32_e32 v71, 0x80000000, v71
	v_xor_b32_e32 v72, 0x80000000, v72
	v_xor_b32_e32 v73, 0x80000000, v73
	v_xor_b32_e32 v74, 0x80000000, v74
	v_xor_b32_e32 v75, 0x80000000, v75
	v_xor_b32_e32 v76, 0x80000000, v76
	v_xor_b32_e32 v77, 0x80000000, v77
	v_xor_b32_e32 v78, 0x80000000, v78
	v_xor_b32_e32 v79, 0x80000000, v79
	v_xor_b32_e32 v80, 0x80000000, v80
	v_xor_b32_e32 v81, 0x80000000, v81
.Lda_nocflip:
	ds_read_b128 v[210:213], v236 offset:0
	ds_read_b128 v[214:217], v236 offset:32
	ds_read_b128 v[218:221], v236 offset:64
	ds_read_b128 v[222:225], v236 offset:96
	v_mfma_f32_32x32x16_bf16 v[48:63], v[226:229], v[194:197], v[48:63]
	ds_read_b128 v[226:229], v235 offset:18464
	v_sub_f32_e32 v98, v98, v241
	v_sub_f32_e32 v99, v99, v241
	v_sub_f32_e32 v100, v100, v241
	v_sub_f32_e32 v101, v101, v241
	v_exp_f32_e32 v98, v98
	v_mfma_f32_32x32x16_bf16 v[32:47], v[230:233], v[194:197], v[32:47]
	ds_read_b128 v[230:233], v235 offset:23072
	v_exp_f32_e32 v99, v99
	v_exp_f32_e32 v100, v100
	v_exp_f32_e32 v101, v101
	s_waitcnt lgkmcnt(5)
	v_mfma_f32_32x32x16_bf16 v[82:97], v[210:213], v[114:117], v[66:81]
	ds_read_b128 v[210:213], v236 offset:8704
	v_add_f32_e32 v191, v191, v98
	v_add_f32_e32 v192, v192, v99
	v_cvt_pk_bf16_f32 v202, v98, v99
	v_add_f32_e32 v191, v191, v100
	v_add_f32_e32 v192, v192, v101
	v_cvt_pk_bf16_f32 v203, v100, v101
	v_mfma_f32_32x32x16_bf16 v[16:31], v[174:177], v[194:197], v[16:31]
	ds_read_b128 v[174:177], v235 offset:27680
	v_sub_f32_e32 v102, v102, v241
	v_sub_f32_e32 v103, v103, v241
	v_sub_f32_e32 v104, v104, v241
	v_sub_f32_e32 v105, v105, v241
	v_exp_f32_e32 v102, v102
	v_mfma_f32_32x32x16_bf16 v[0:15], v[246:249], v[194:197], v[0:15]
	ds_read_b128 v[246:249], v235 offset:32288
	v_exp_f32_e32 v103, v103
	v_exp_f32_e32 v104, v104
	v_exp_f32_e32 v105, v105
	s_waitcnt lgkmcnt(7)
	v_mfma_f32_32x32x16_bf16 v[82:97], v[214:217], v[118:121], v[82:97]
	ds_read_b128 v[214:217], v236 offset:8736
	v_add_f32_e32 v191, v191, v102
	v_add_f32_e32 v192, v192, v103
	v_cvt_pk_bf16_f32 v204, v102, v103
	v_add_f32_e32 v191, v191, v104
	v_add_f32_e32 v192, v192, v105
	v_cvt_pk_bf16_f32 v205, v104, v105
	s_waitcnt lgkmcnt(5)
	v_mfma_f32_32x32x16_bf16 v[48:63], v[226:229], v[198:201], v[48:63]
	ds_read_b128 v[226:229], v235 offset:18496
	v_sub_f32_e32 v106, v106, v241
	v_sub_f32_e32 v107, v107, v241
	v_sub_f32_e32 v108, v108, v241
	v_sub_f32_e32 v109, v109, v241
	v_exp_f32_e32 v106, v106
	s_waitcnt lgkmcnt(5)
	v_mfma_f32_32x32x16_bf16 v[32:47], v[230:233], v[198:201], v[32:47]
	ds_read_b128 v[230:233], v235 offset:23104
	v_exp_f32_e32 v107, v107
	v_exp_f32_e32 v108, v108
	v_exp_f32_e32 v109, v109
	v_mfma_f32_32x32x16_bf16 v[82:97], v[218:221], v[122:125], v[82:97]
	ds_read_b128 v[218:221], v236 offset:8768
	v_add_f32_e32 v191, v191, v106
	v_add_f32_e32 v192, v192, v107
	v_cvt_pk_bf16_f32 v206, v106, v107
	v_add_f32_e32 v191, v191, v108
	v_add_f32_e32 v192, v192, v109
	v_cvt_pk_bf16_f32 v207, v108, v109
	s_waitcnt lgkmcnt(5)
	v_mfma_f32_32x32x16_bf16 v[16:31], v[174:177], v[198:201], v[16:31]
	ds_read_b128 v[174:177], v235 offset:27712
	v_sub_f32_e32 v110, v110, v241
	v_sub_f32_e32 v111, v111, v241
	v_sub_f32_e32 v112, v112, v241
	v_sub_f32_e32 v113, v113, v241
	v_exp_f32_e32 v110, v110
	s_waitcnt lgkmcnt(5)
	v_mfma_f32_32x32x16_bf16 v[0:15], v[246:249], v[198:201], v[0:15]
	ds_read_b128 v[246:249], v235 offset:32320
	v_exp_f32_e32 v111, v111
	v_exp_f32_e32 v112, v112
	v_exp_f32_e32 v113, v113
	v_mfma_f32_32x32x16_bf16 v[82:97], v[222:225], v[126:129], v[82:97]
	ds_read_b128 v[222:225], v236 offset:8800
	v_add_f32_e32 v191, v191, v110
	v_add_f32_e32 v192, v192, v111
	v_cvt_pk_bf16_f32 v208, v110, v111
	v_add_f32_e32 v191, v191, v112
	v_add_f32_e32 v192, v192, v113
	v_cvt_pk_bf16_f32 v209, v112, v113
	s_add_i32 s4, s4, 1
	s_cmp_lt_u32 s4, 16
	s_waitcnt lgkmcnt(0)
	s_cbranch_scc1 .Lda_top
	v_mfma_f32_32x32x16_bf16 v[48:63], v[226:229], v[202:205], v[48:63]
	ds_read_b128 v[226:229], v235 offset:18528
	v_mfma_f32_32x32x16_bf16 v[32:47], v[230:233], v[202:205], v[32:47]
	ds_read_b128 v[230:233], v235 offset:23136
	v_mfma_f32_32x32x16_bf16 v[16:31], v[174:177], v[202:205], v[16:31]
	ds_read_b128 v[174:177], v235 offset:27744
	v_mfma_f32_32x32x16_bf16 v[0:15], v[246:249], v[202:205], v[0:15]
	ds_read_b128 v[246:249], v235 offset:32352
	s_waitcnt lgkmcnt(3)
	v_mfma_f32_32x32x16_bf16 v[48:63], v[226:229], v[206:209], v[48:63]
	s_waitcnt lgkmcnt(2)
	v_mfma_f32_32x32x16_bf16 v[32:47], v[230:233], v[206:209], v[32:47]
	s_waitcnt lgkmcnt(1)
	v_mfma_f32_32x32x16_bf16 v[16:31], v[174:177], v[206:209], v[16:31]
	s_waitcnt lgkmcnt(0)
	v_mfma_f32_32x32x16_bf16 v[0:15], v[246:249], v[206:209], v[0:15]
	v_add_f32_e32 v191, v191, v192
	s_nop 7
	s_nop 3
	v_add_f32_e32 v193, v193, v191
.LBB0_496:
	v_add_f32_e32 v64, v170, v172
	v_add_f32_e32 v67, v171, v173
	v_mul_f32_e32 v64, 0x3fb8aa3b, v64
	v_mul_f32_e32 v67, 0x3fb8aa3b, v67
	v_exp_f32_e32 v191, v67
	v_exp_f32_e32 v192, v64
	s_mov_b64 s[0:1], 0x2000
	v_lshl_add_u64 v[112:113], v[164:165], 0, s[0:1]
	v_lshl_add_u64 v[170:171], v[166:167], 0, s[0:1]
	s_mov_b64 s[0:1], 0x4000
	v_lshl_add_u64 v[172:173], v[164:165], 0, s[0:1]
	v_lshl_add_u64 v[174:175], v[166:167], 0, s[0:1]
	s_mov_b64 s[0:1], 0x6000
	v_lshl_add_u64 v[176:177], v[164:165], 0, s[0:1]
	v_lshl_add_u64 v[178:179], v[166:167], 0, s[0:1]
	s_branch .LBB0_505
